# GEMM1: workgroups 128..255 (no ninth tile) start half a tile late so the two halves of every XCD alternate K loops and store-burst epilogues
# speedup vs baseline: 1.0406x; 1.0095x over previous
.LBB0_106:
	v_writelane_b32 v246, s52, 32
	s_nop 1
	v_writelane_b32 v246, s53, 33
	v_writelane_b32 v246, s54, 34
	v_writelane_b32 v246, s55, 35
	v_writelane_b32 v246, s56, 36
	v_writelane_b32 v246, s57, 37
	v_writelane_b32 v246, s58, 38
	v_writelane_b32 v246, s59, 39
	v_writelane_b32 v246, s60, 40
	v_writelane_b32 v246, s61, 41
	v_writelane_b32 v246, s62, 42
	v_writelane_b32 v246, s63, 43
	v_writelane_b32 v246, s64, 44
	v_writelane_b32 v246, s65, 45
	v_writelane_b32 v246, s66, 46
	v_writelane_b32 v246, s67, 47
	s_or_b64 exec, exec, s[18:19]
	s_bitcmp0_b32 s2, 7
	s_cbranch_scc1 .Lg1d_skip
	s_sleep 127
	s_sleep 127
	s_sleep 127
.Lg1d_skip:
	s_cmpk_lt_i32 s2, 0x880
	s_cselect_b64 s[18:19], -1, 0
	v_readfirstlane_b32 s22, v141
	s_and_b64 vcc, exec, s[18:19]
	s_waitcnt lgkmcnt(0)
	s_barrier
	s_cbranch_vccz .LBB0_108
	s_and_b32 s23, s2, 7
	s_lshr_b32 s24, s2, 3
	s_lshl_b32 s23, s23, 8
	s_add_i32 s23, s23, s24
	s_lshr_b32 s24, s23, 7
	s_lshl_b32 s24, s24, 3
	s_and_b32 s25, s23, 7
	s_add_i32 s38, s24, s25
	s_bfe_u32 s54, s23, 0x40003
